# top-k rank count rewritten: cmp into rotating SGPR pairs + addc (no hazard nops), stops at the first 8-entry boundary past the causal block
# speedup vs baseline: 1.0290x; 1.0005x over previous
; #define LAS __attribute__((address_space(3)))
; #define LDS_WAIT() asm volatile("s_waitcnt lgkmcnt(0)" ::: "memory")
; __device__ __forceinline__ void nsa_unit(const Params& p, LAS unsigned char* lds, int b, int hkv, int i, int tid, int lane, int wave) {
;     ...
;             float v = impw[q * 64 + n] + (n > 0 ? impw3[q * 64 + n - 1] : 0.f) + ((n == 0 || n == i || n == i - 1) ? 1.0e4f : 0.f);
;             v = (n <= i) ? v : -1.0e9f;
;             vbuf[n] = v;
;             LDS_WAIT();
;             int cgt = 0;
; #pragma unroll
;             for (int m4 = 0; m4 < 16; ++m4) { const f32x4 w = *(const LAS f32x4*)(vbuf + 4 * m4); cgt += (w.x > v ? 1 : 0) + (w.y > v ? 1 : 0) + (w.z > v ? 1 : 0) + (w.w > v ? 1 : 0); }
;             LDS_WAIT();
;             unsigned long long sel = __ballot(cgt < 16) & curmask;
.LBB0_493:
	v_lshlrev_b32_e32 v2, 2, v124
	v_lshl_or_b32 v2, s4, 8, v2
	v_add_u32_e32 v8, s17, v2
	ds_read_b32 v2, v8
	v_mov_b32_e32 v7, 0
	s_and_saveexec_b64 s[10:11], s[18:19]
	ds_read_b32 v7, v8 offset:2044
	s_or_b64 exec, exec, s[10:11]
	s_waitcnt lgkmcnt(0)
	v_add_f32_e32 v2, v2, v7
	v_add_f32_e32 v2, v4, v2
	v_cndmask_b32_e64 v2, v2, v199, s[20:21]
	ds_write_b32 v6, v2
	s_waitcnt lgkmcnt(0)
	v_mov_b32_e32 v19, s33
	v_mov_b32_e32 v7, 0
	ds_read_b128 v[8:11], v19
	ds_read_b128 v[12:15], v19 offset:16
	ds_read_b128 v[52:55], v19 offset:32
	ds_read_b128 v[56:59], v19 offset:48
	s_waitcnt lgkmcnt(3)
	v_cmp_gt_f32_e64 s[22:23], v8, v2
	v_cmp_gt_f32_e64 s[24:25], v9, v2
	v_cmp_gt_f32_e64 s[26:27], v10, v2
	v_addc_co_u32_e64 v7, s[22:23], 0, v7, s[22:23]
	v_cmp_gt_f32_e64 s[22:23], v11, v2
	ds_read_b128 v[8:11], v19 offset:64
	v_addc_co_u32_e64 v7, s[24:25], 0, v7, s[24:25]
	s_waitcnt lgkmcnt(3)
	v_cmp_gt_f32_e64 s[24:25], v12, v2
	v_addc_co_u32_e64 v7, s[26:27], 0, v7, s[26:27]
	v_cmp_gt_f32_e64 s[26:27], v13, v2
	v_addc_co_u32_e64 v7, s[22:23], 0, v7, s[22:23]
	v_cmp_gt_f32_e64 s[22:23], v14, v2
	v_addc_co_u32_e64 v7, s[24:25], 0, v7, s[24:25]
	v_cmp_gt_f32_e64 s[24:25], v15, v2
	ds_read_b128 v[12:15], v19 offset:80
	v_addc_co_u32_e64 v7, s[26:27], 0, v7, s[26:27]
	s_waitcnt lgkmcnt(3)
	v_cmp_gt_f32_e64 s[26:27], v52, v2
	v_addc_co_u32_e64 v7, s[22:23], 0, v7, s[22:23]
	v_cmp_gt_f32_e64 s[22:23], v53, v2
	v_addc_co_u32_e64 v7, s[24:25], 0, v7, s[24:25]
	v_cmp_gt_f32_e64 s[24:25], v54, v2
	v_addc_co_u32_e64 v7, s[26:27], 0, v7, s[26:27]
	v_cmp_gt_f32_e64 s[26:27], v55, v2
	ds_read_b128 v[52:55], v19 offset:96
	v_addc_co_u32_e64 v7, s[22:23], 0, v7, s[22:23]
	s_waitcnt lgkmcnt(3)
	v_cmp_gt_f32_e64 s[22:23], v56, v2
	v_addc_co_u32_e64 v7, s[24:25], 0, v7, s[24:25]
	v_cmp_gt_f32_e64 s[24:25], v57, v2
	v_addc_co_u32_e64 v7, s[26:27], 0, v7, s[26:27]
	v_cmp_gt_f32_e64 s[26:27], v58, v2
	v_addc_co_u32_e64 v7, s[22:23], 0, v7, s[22:23]
	v_cmp_gt_f32_e64 s[22:23], v59, v2
	ds_read_b128 v[56:59], v19 offset:112
	v_addc_co_u32_e64 v7, s[24:25], 0, v7, s[24:25]
	s_waitcnt lgkmcnt(3)
	v_cmp_gt_f32_e64 s[24:25], v8, v2
	v_addc_co_u32_e64 v7, s[26:27], 0, v7, s[26:27]
	v_cmp_gt_f32_e64 s[26:27], v9, v2
	v_addc_co_u32_e64 v7, s[22:23], 0, v7, s[22:23]
	v_cmp_gt_f32_e64 s[22:23], v10, v2
	v_addc_co_u32_e64 v7, s[24:25], 0, v7, s[24:25]
	v_cmp_gt_f32_e64 s[24:25], v11, v2
	ds_read_b128 v[8:11], v19 offset:128
	v_addc_co_u32_e64 v7, s[26:27], 0, v7, s[26:27]
	s_waitcnt lgkmcnt(3)
	v_cmp_gt_f32_e64 s[26:27], v12, v2
	v_addc_co_u32_e64 v7, s[22:23], 0, v7, s[22:23]
	v_cmp_gt_f32_e64 s[22:23], v13, v2
	v_addc_co_u32_e64 v7, s[24:25], 0, v7, s[24:25]
	v_cmp_gt_f32_e64 s[24:25], v14, v2
	v_addc_co_u32_e64 v7, s[26:27], 0, v7, s[26:27]
	v_cmp_gt_f32_e64 s[26:27], v15, v2
	ds_read_b128 v[12:15], v19 offset:144
	v_addc_co_u32_e64 v7, s[22:23], 0, v7, s[22:23]
	v_addc_co_u32_e64 v7, s[24:25], 0, v7, s[24:25]
	v_addc_co_u32_e64 v7, s[26:27], 0, v7, s[26:27]
	s_cmp_lt_u32 s67, 24
	s_cbranch_scc1 .Ltk_done
	s_waitcnt lgkmcnt(3)
	v_cmp_gt_f32_e64 s[22:23], v52, v2
	v_cmp_gt_f32_e64 s[24:25], v53, v2
	v_cmp_gt_f32_e64 s[26:27], v54, v2
	v_addc_co_u32_e64 v7, s[22:23], 0, v7, s[22:23]
	v_cmp_gt_f32_e64 s[22:23], v55, v2
	ds_read_b128 v[52:55], v19 offset:160
	v_addc_co_u32_e64 v7, s[24:25], 0, v7, s[24:25]
	s_waitcnt lgkmcnt(3)
	v_cmp_gt_f32_e64 s[24:25], v56, v2
	v_addc_co_u32_e64 v7, s[26:27], 0, v7, s[26:27]
	v_cmp_gt_f32_e64 s[26:27], v57, v2
	v_addc_co_u32_e64 v7, s[22:23], 0, v7, s[22:23]
	v_cmp_gt_f32_e64 s[22:23], v58, v2
	v_addc_co_u32_e64 v7, s[24:25], 0, v7, s[24:25]
	v_cmp_gt_f32_e64 s[24:25], v59, v2
	ds_read_b128 v[56:59], v19 offset:176
	v_addc_co_u32_e64 v7, s[26:27], 0, v7, s[26:27]
	v_addc_co_u32_e64 v7, s[22:23], 0, v7, s[22:23]
	v_addc_co_u32_e64 v7, s[24:25], 0, v7, s[24:25]
	s_cmp_lt_u32 s67, 32
	s_cbranch_scc1 .Ltk_done
; #define LAS __attribute__((address_space(3)))
; #define LDS_WAIT() asm volatile("s_waitcnt lgkmcnt(0)" ::: "memory")
; __device__ __forceinline__ void nsa_unit(const Params& p, LAS unsigned char* lds, int b, int hkv, int i, int tid, int lane, int wave) {
;     ...
;             int cgt = 0;
; #pragma unroll
;             for (int m4 = 0; m4 < 16; ++m4) { const f32x4 w = *(const LAS f32x4*)(vbuf + 4 * m4); cgt += (w.x > v ? 1 : 0) + (w.y > v ? 1 : 0) + (w.z > v ? 1 : 0) + (w.w > v ? 1 : 0); }
;             LDS_WAIT();
;             unsigned long long sel = __ballot(cgt < 16) & curmask;
;             if (__builtin_popcountll(sel) != want) {
;                 int rank = 0;
; #pragma unroll 8
;                 for (int mm = 0; mm < 64; ++mm) { const float vm = vbuf[mm]; rank += (vm > v || (vm == v && mm < n)) ? 1 : 0; }
;                 LDS_WAIT();
;                 sel = __ballot(rank < 16) & curmask;
;             }
	s_waitcnt lgkmcnt(3)
	v_cmp_gt_f32_e64 s[26:27], v8, v2
	v_cmp_gt_f32_e64 s[22:23], v9, v2
	v_cmp_gt_f32_e64 s[24:25], v10, v2
	v_addc_co_u32_e64 v7, s[26:27], 0, v7, s[26:27]
	v_cmp_gt_f32_e64 s[26:27], v11, v2
	ds_read_b128 v[8:11], v19 offset:192
	v_addc_co_u32_e64 v7, s[22:23], 0, v7, s[22:23]
	s_waitcnt lgkmcnt(3)
	v_cmp_gt_f32_e64 s[22:23], v12, v2
	v_addc_co_u32_e64 v7, s[24:25], 0, v7, s[24:25]
	v_cmp_gt_f32_e64 s[24:25], v13, v2
	v_addc_co_u32_e64 v7, s[26:27], 0, v7, s[26:27]
	v_cmp_gt_f32_e64 s[26:27], v14, v2
	v_addc_co_u32_e64 v7, s[22:23], 0, v7, s[22:23]
	v_cmp_gt_f32_e64 s[22:23], v15, v2
	ds_read_b128 v[12:15], v19 offset:208
	v_addc_co_u32_e64 v7, s[24:25], 0, v7, s[24:25]
	v_addc_co_u32_e64 v7, s[26:27], 0, v7, s[26:27]
	v_addc_co_u32_e64 v7, s[22:23], 0, v7, s[22:23]
	s_cmp_lt_u32 s67, 40
	s_cbranch_scc1 .Ltk_done
	s_waitcnt lgkmcnt(3)
	v_cmp_gt_f32_e64 s[24:25], v52, v2
	v_cmp_gt_f32_e64 s[26:27], v53, v2
	v_cmp_gt_f32_e64 s[22:23], v54, v2
	v_addc_co_u32_e64 v7, s[24:25], 0, v7, s[24:25]
	v_cmp_gt_f32_e64 s[24:25], v55, v2
	ds_read_b128 v[52:55], v19 offset:224
	v_addc_co_u32_e64 v7, s[26:27], 0, v7, s[26:27]
	s_waitcnt lgkmcnt(3)
	v_cmp_gt_f32_e64 s[26:27], v56, v2
	v_addc_co_u32_e64 v7, s[22:23], 0, v7, s[22:23]
	v_cmp_gt_f32_e64 s[22:23], v57, v2
	v_addc_co_u32_e64 v7, s[24:25], 0, v7, s[24:25]
	v_cmp_gt_f32_e64 s[24:25], v58, v2
	v_addc_co_u32_e64 v7, s[26:27], 0, v7, s[26:27]
	v_cmp_gt_f32_e64 s[26:27], v59, v2
	ds_read_b128 v[56:59], v19 offset:240
	v_addc_co_u32_e64 v7, s[22:23], 0, v7, s[22:23]
	v_addc_co_u32_e64 v7, s[24:25], 0, v7, s[24:25]
	v_addc_co_u32_e64 v7, s[26:27], 0, v7, s[26:27]
	s_cmp_lt_u32 s67, 48
	s_cbranch_scc1 .Ltk_done
	s_waitcnt lgkmcnt(3)
	v_cmp_gt_f32_e64 s[22:23], v8, v2
	v_cmp_gt_f32_e64 s[24:25], v9, v2
	v_cmp_gt_f32_e64 s[26:27], v10, v2
	v_addc_co_u32_e64 v7, s[22:23], 0, v7, s[22:23]
	v_cmp_gt_f32_e64 s[22:23], v11, v2
	v_addc_co_u32_e64 v7, s[24:25], 0, v7, s[24:25]
	s_waitcnt lgkmcnt(2)
	v_cmp_gt_f32_e64 s[24:25], v12, v2
	v_addc_co_u32_e64 v7, s[26:27], 0, v7, s[26:27]
	v_cmp_gt_f32_e64 s[26:27], v13, v2
	v_addc_co_u32_e64 v7, s[22:23], 0, v7, s[22:23]
	v_cmp_gt_f32_e64 s[22:23], v14, v2
	v_addc_co_u32_e64 v7, s[24:25], 0, v7, s[24:25]
	v_cmp_gt_f32_e64 s[24:25], v15, v2
	v_addc_co_u32_e64 v7, s[26:27], 0, v7, s[26:27]
	v_addc_co_u32_e64 v7, s[22:23], 0, v7, s[22:23]
	v_addc_co_u32_e64 v7, s[24:25], 0, v7, s[24:25]
	s_cmp_lt_u32 s67, 56
	s_cbranch_scc1 .Ltk_done
	s_waitcnt lgkmcnt(1)
	v_cmp_gt_f32_e64 s[26:27], v52, v2
	v_cmp_gt_f32_e64 s[22:23], v53, v2
	v_cmp_gt_f32_e64 s[24:25], v54, v2
	v_addc_co_u32_e64 v7, s[26:27], 0, v7, s[26:27]
	v_cmp_gt_f32_e64 s[26:27], v55, v2
	v_addc_co_u32_e64 v7, s[22:23], 0, v7, s[22:23]
	s_waitcnt lgkmcnt(0)
	v_cmp_gt_f32_e64 s[22:23], v56, v2
	v_addc_co_u32_e64 v7, s[24:25], 0, v7, s[24:25]
	v_cmp_gt_f32_e64 s[24:25], v57, v2
	v_addc_co_u32_e64 v7, s[26:27], 0, v7, s[26:27]
	v_cmp_gt_f32_e64 s[26:27], v58, v2
	v_addc_co_u32_e64 v7, s[22:23], 0, v7, s[22:23]
	v_cmp_gt_f32_e64 s[22:23], v59, v2
	v_addc_co_u32_e64 v7, s[24:25], 0, v7, s[24:25]
	v_addc_co_u32_e64 v7, s[26:27], 0, v7, s[26:27]
	v_addc_co_u32_e64 v7, s[22:23], 0, v7, s[22:23]
.Ltk_done:
	s_waitcnt lgkmcnt(0)
	v_cmp_gt_u32_e64 s[22:23], 16, v7
	s_and_b64 s[10:11], s[22:23], s[2:3]
	s_bcnt1_i32_b64 s5, s[10:11]
	s_cmp_eq_u32 s0, s5
	s_cbranch_scc1 .LBB0_492
	v_mov_b32_e32 v7, v2
	s_mov_b32 s5, 1
	s_mov_b32 s8, 0
	v_mov_b32_e32 v9, 0
	v_mov_b32_e32 v8, 0
	s_mov_b32 s9, 0
